# scan loop vmcnt waits made exact (27/17 instead of 19/13): no longer wait on stores and loads younger than the guarded data
# baseline (speedup 1.0000x reference)
; __device__ __forceinline__ uint2 pack4v(f32x4 a) { uint2 r; r.x = pack2(a[0], a[1]); r.y = pack2(a[2], a[3]); return r; }
; __device__ __forceinline__ f32x4 mfma16(bf16x8 a, bf16x8 b, f32x4 c) { return __builtin_amdgcn_mfma_f32_16x16x32_bf16(a, b, c, 0, 0, 0); }
; __device__ __forceinline__ void scan_step(const ScanCtx& c, int n, const u16* Sc, u16* Sn, f32x4 (&S)[4], bf16x8 (&W_)[2], ...
;   const int w = c.w, lane = c.lane;
;   const size_t cb = (size_t)(c.seq * 128 + n) * 4096;
;   bf16x8 Sf[2][4];
; #pragma unroll
;   for (int kb = 0; kb < 2; ++kb)
; #pragma unroll
;     for (int nt = 0; nt < 4; ++nt) Sf[kb][nt] = *(const bf16x8*)(Sc + ((kb * 4 + nt) * 64 + lane) * 8);
; #pragma unroll
;   for (int nt = 0; nt < 4; ++nt) {
;     f32x4 a = {0.f, 0.f, 0.f, 0.f};
;     a = mfma16(W_[0], Sf[0][nt], a); a = mfma16(W_[1], Sf[1][nt], a);
;     f32x4 vn = U_[nt] - a;
;     *(uint2*)(c.Vbuf + (((w >> 1) * 4 + nt) * 64 + lane) * 8 + (w & 1) * 4) = pack4v(vn);
;   }
;   __syncthreads();
;   bf16x8 Vf[2][4];
; #pragma unroll
;   for (int kb = 0; kb < 2; ++kb)
; #pragma unroll
;     for (int nt = 0; nt < 4; ++nt) Vf[kb][nt] = *(const bf16x8*)(c.Vbuf + ((kb * 4 + nt) * 64 + lane) * 8);
;   const float glc = g_;
; #pragma unroll
;   for (int nt = 0; nt < 4; ++nt) {
;     f32x4 o = {0.f, 0.f, 0.f, 0.f};
;     o = mfma16(QH_[0], Sf[0][nt], o); o = mfma16(QH_[1], Sf[1][nt], o);
;     o = mfma16(QK_[0], Vf[0][nt], o); o = mfma16(QK_[1], Vf[1][nt], o);
;     *(f32x4*)(c.Obuf + cb + ((w * 4 + nt) * 64 + lane) * 4) = o;
;     f32x4 sv = S[nt] * glc;
;     sv = mfma16(KT_[0], Vf[0][nt], sv); sv = mfma16(KT_[1], Vf[1][nt], sv);
;     S[nt] = sv;
;     *(uint2*)(Sn + (((w >> 1) * 4 + nt) * 64 + lane) * 8 + (w & 1) * 4) = pack4v(sv);
;   }
.LBB0_483:
	ds_read_b128 v[130:133], v126
	ds_read_b128 v[134:137], v126 offset:1024
	ds_read_b128 v[142:145], v126 offset:2048
	ds_read_b128 v[146:149], v126 offset:3072
	ds_read_b128 v[150:153], v126 offset:4096
	ds_read_b128 v[158:161], v126 offset:5120
	ds_read_b128 v[162:165], v126 offset:6144
	ds_read_b128 v[166:169], v126 offset:7168
	s_waitcnt vmcnt(27)
	v_mov_b32_e32 v52, v170
	v_mov_b32_e32 v53, v171
	v_mov_b32_e32 v54, v172
	v_mov_b32_e32 v55, v173
	v_mov_b32_e32 v48, v174
	v_mov_b32_e32 v49, v175
	v_mov_b32_e32 v50, v176
	v_mov_b32_e32 v51, v177
	v_mov_b32_e32 v76, v178
	v_mov_b32_e32 v77, v179
	v_mov_b32_e32 v78, v180
	v_mov_b32_e32 v79, v181
	v_mov_b32_e32 v72, v182
	v_mov_b32_e32 v73, v183
	v_mov_b32_e32 v74, v184
	v_mov_b32_e32 v75, v185
	v_mov_b32_e32 v68, v186
	v_mov_b32_e32 v69, v187
	v_mov_b32_e32 v70, v188
	v_mov_b32_e32 v71, v189
	v_mov_b32_e32 v64, v190
	v_mov_b32_e32 v65, v191
	v_mov_b32_e32 v66, v192
	v_mov_b32_e32 v67, v193
	v_mov_b32_e32 v118, v194
	v_pk_mul_f32 v[102:103], v[102:103], v[118:119] op_sel_hi:[1,0]
	s_waitcnt lgkmcnt(7)
	v_mfma_f32_16x16x32_bf16 v[138:141], v[52:55], v[130:133], 0
	v_mul_f32_e64 v100, v100, v118
	v_mul_f32_e64 v101, v101, v118
	s_add_i32 s13, s12, 2
	s_waitcnt lgkmcnt(3)
	v_mfma_f32_16x16x32_bf16 v[138:141], v[48:51], v[150:153], v[138:141]
	v_mfma_f32_16x16x32_bf16 v[154:157], v[52:55], v[134:137], 0
	s_nop 6
	v_sub_f32_e32 v79, v79, v141
	v_sub_f32_e32 v78, v78, v140
	v_sub_f32_e32 v77, v77, v139
	v_sub_f32_e32 v76, v76, v138
	v_cvt_pk_bf16_f32 v138, v76, v77
	v_cvt_pk_bf16_f32 v139, v78, v79
	s_waitcnt lgkmcnt(2)
	v_mfma_f32_16x16x32_bf16 v[76:79], v[48:51], v[158:161], v[154:157]
	s_nop 7
	v_sub_f32_e32 v79, v75, v79
	v_sub_f32_e32 v78, v74, v78
	v_sub_f32_e32 v77, v73, v77
	v_sub_f32_e32 v76, v72, v76
	v_mfma_f32_16x16x32_bf16 v[72:75], v[52:55], v[142:145], 0
	v_cvt_pk_bf16_f32 v76, v76, v77
	v_cvt_pk_bf16_f32 v77, v78, v79
	ds_write2st64_b64 v127, v[138:139], v[76:77] offset0:32 offset1:34
	v_mfma_f32_16x16x32_bf16 v[52:55], v[52:55], v[146:149], 0
	v_mul_f32_e64 v78, v110, v118
	v_mul_f32_e64 v79, v111, v118
	v_pk_mul_f32 v[76:77], v[108:109], v[118:119] op_sel_hi:[1,0]
	s_waitcnt lgkmcnt(2)
	v_mfma_f32_16x16x32_bf16 v[72:75], v[48:51], v[162:165], v[72:75]
	s_waitcnt lgkmcnt(1)
	v_mfma_f32_16x16x32_bf16 v[48:51], v[48:51], v[166:169], v[52:55]
	s_nop 5
	v_sub_f32_e32 v71, v71, v75
	v_sub_f32_e32 v70, v70, v74
	v_sub_f32_e32 v69, v69, v73
	v_sub_f32_e32 v68, v68, v72
	v_sub_f32_e32 v51, v67, v51
	v_sub_f32_e32 v50, v66, v50
	v_sub_f32_e32 v49, v65, v49
	v_sub_f32_e32 v48, v64, v48
	v_cvt_pk_bf16_f32 v68, v68, v69
	v_cvt_pk_bf16_f32 v69, v70, v71
	v_cvt_pk_bf16_f32 v48, v48, v49
	v_cvt_pk_bf16_f32 v49, v50, v51
	ds_write_b64 v128, v[68:69] offset:16384
	ds_write_b64 v129, v[48:49] offset:16384
	s_waitcnt vmcnt(17)
	v_mfma_f32_16x16x32_bf16 v[48:51], v[4:7], v[130:133], 0
	s_waitcnt lgkmcnt(0)
	s_barrier
	s_min_u32 s24, s13, 0x7d
	s_add_i32 s24, s24, s8
	s_ashr_i32 s25, s24, 31
	s_lshl_b64 s[26:27], s[24:25], 12
	v_lshl_add_u64 v[222:223], s[26:27], 0, v[112:113]
	v_lshlrev_b64 v[222:223], 1, v[222:223]
	v_lshl_add_u64 v[222:223], s[20:21], 0, v[222:223]
	s_lshl_b64 s[26:27], s[24:25], 14
	v_lshl_add_u64 v[224:225], v[116:117], 0, s[26:27]
	s_lshl_b64 s[28:29], s[24:25], 2
	s_add_u32 s28, s10, s28
	s_addc_u32 s29, s11, s29
	global_load_dwordx4 v[170:173], v[222:223], off
	global_load_dwordx4 v[174:177], v[222:223], off offset:1024
	global_load_dwordx4 v[178:181], v[224:225], off
	global_load_dwordx4 v[182:185], v[224:225], off offset:1024
	global_load_dwordx4 v[186:189], v[224:225], off offset:2048
	global_load_dwordx4 v[190:193], v[224:225], off offset:3072
	global_load_dword v194, v125, s[28:29]
	v_mfma_f32_16x16x32_bf16 v[48:51], v[16:19], v[150:153], v[48:51]
	ds_read_b128 v[52:55], v126 offset:16384
	ds_read_b128 v[64:67], v126 offset:17408
	ds_read_b128 v[68:71], v126 offset:20480
	ds_read_b128 v[72:75], v126 offset:21504
	s_waitcnt lgkmcnt(3)
	v_mfma_f32_16x16x32_bf16 v[48:51], v[0:3], v[52:55], v[48:51]
	v_mfma_f32_16x16x32_bf16 v[52:55], v[8:11], v[52:55], v[76:79]
	s_waitcnt lgkmcnt(1)
	v_mfma_f32_16x16x32_bf16 v[108:111], v[12:15], v[68:71], v[52:55]
	v_mfma_f32_16x16x32_bf16 v[52:55], v[4:7], v[134:137], 0
	v_mfma_f32_16x16x32_bf16 v[52:55], v[16:19], v[158:161], v[52:55]
	v_mfma_f32_16x16x32_bf16 v[48:51], v[20:23], v[68:71], v[48:51]
	v_mul_f32_e64 v70, v106, v118
	v_mul_f32_e64 v71, v107, v118
	v_pk_mul_f32 v[68:69], v[104:105], v[118:119] op_sel_hi:[1,0]
	v_mfma_f32_16x16x32_bf16 v[52:55], v[0:3], v[64:67], v[52:55]
	s_nop 0
	v_mfma_f32_16x16x32_bf16 v[64:67], v[8:11], v[64:67], v[68:71]
	s_waitcnt lgkmcnt(0)
	v_mfma_f32_16x16x32_bf16 v[104:107], v[12:15], v[72:75], v[64:67]
	v_mfma_f32_16x16x32_bf16 v[64:67], v[4:7], v[142:145], 0
	v_mfma_f32_16x16x32_bf16 v[4:7], v[4:7], v[146:149], 0
	v_mfma_f32_16x16x32_bf16 v[52:55], v[20:23], v[72:75], v[52:55]
	ds_read_b128 v[68:71], v126 offset:18432
	ds_read_b128 v[72:75], v126 offset:19456
	ds_read_b128 v[76:79], v126 offset:22528
	ds_read_b128 v[130:133], v126 offset:23552
	v_mfma_f32_16x16x32_bf16 v[64:67], v[16:19], v[162:165], v[64:67]
	v_mfma_f32_16x16x32_bf16 v[4:7], v[16:19], v[166:169], v[4:7]
	v_cvt_pk_bf16_f32 v16, v104, v105
	v_cvt_pk_bf16_f32 v17, v106, v107
	s_waitcnt lgkmcnt(3)
	v_mfma_f32_16x16x32_bf16 v[64:67], v[0:3], v[68:71], v[64:67]
	s_waitcnt lgkmcnt(2)
	v_mfma_f32_16x16x32_bf16 v[0:3], v[0:3], v[72:75], v[4:7]
	s_nop 2
	v_mul_f32_e64 v6, v98, v118
	v_mul_f32_e64 v7, v99, v118
	v_pk_mul_f32 v[4:5], v[96:97], v[118:119] op_sel_hi:[1,0]
	v_mfma_f32_16x16x32_bf16 v[68:71], v[8:11], v[68:71], v[100:103]
	s_nop 0
	v_mfma_f32_16x16x32_bf16 v[4:7], v[8:11], v[72:75], v[4:7]
	s_waitcnt lgkmcnt(1)
; __device__ __forceinline__ uint2 pack4v(f32x4 a) { uint2 r; r.x = pack2(a[0], a[1]); r.y = pack2(a[2], a[3]); return r; }
; __device__ __forceinline__ f32x4 mfma16(bf16x8 a, bf16x8 b, f32x4 c) { return __builtin_amdgcn_mfma_f32_16x16x32_bf16(a, b, c, 0, 0, 0); }
; __device__ __forceinline__ void scan_step(const ScanCtx& c, int n, const u16* Sc, u16* Sn, f32x4 (&S)[4], bf16x8 (&W_)[2], ...
;   const int w = c.w, lane = c.lane;
;   const size_t cb = (size_t)(c.seq * 128 + n) * 4096;
;   bf16x8 Sf[2][4];
; #pragma unroll
;   for (int kb = 0; kb < 2; ++kb)
; #pragma unroll
;     for (int nt = 0; nt < 4; ++nt) Sf[kb][nt] = *(const bf16x8*)(Sc + ((kb * 4 + nt) * 64 + lane) * 8);
; #pragma unroll
;   for (int nt = 0; nt < 4; ++nt) {
;     f32x4 a = {0.f, 0.f, 0.f, 0.f};
;     a = mfma16(W_[0], Sf[0][nt], a); a = mfma16(W_[1], Sf[1][nt], a);
;     f32x4 vn = U_[nt] - a;
;     *(uint2*)(c.Vbuf + (((w >> 1) * 4 + nt) * 64 + lane) * 8 + (w & 1) * 4) = pack4v(vn);
;   }
;   __syncthreads();
;   bf16x8 Vf[2][4];
; #pragma unroll
;   for (int kb = 0; kb < 2; ++kb)
; #pragma unroll
;     for (int nt = 0; nt < 4; ++nt) Vf[kb][nt] = *(const bf16x8*)(c.Vbuf + ((kb * 4 + nt) * 64 + lane) * 8);
;   const float glc = g_;
; #pragma unroll
;   for (int nt = 0; nt < 4; ++nt) {
;     f32x4 o = {0.f, 0.f, 0.f, 0.f};
;     o = mfma16(QH_[0], Sf[0][nt], o); o = mfma16(QH_[1], Sf[1][nt], o);
;     o = mfma16(QK_[0], Vf[0][nt], o); o = mfma16(QK_[1], Vf[1][nt], o);
;     *(f32x4*)(c.Obuf + cb + ((w * 4 + nt) * 64 + lane) * 4) = o;
;     f32x4 sv = S[nt] * glc;
;     sv = mfma16(KT_[0], Vf[0][nt], sv); sv = mfma16(KT_[1], Vf[1][nt], sv);
;     S[nt] = sv;
;     *(uint2*)(Sn + (((w >> 1) * 4 + nt) * 64 + lane) * 8 + (w & 1) * 4) = pack4v(sv);
;   }
;   __builtin_amdgcn_sched_barrier(0);
;   scan_load(c, n + 2, W_, QH_, QK_, KT_, U_, g_);
	v_mfma_f32_16x16x32_bf16 v[100:103], v[12:15], v[76:79], v[68:71]
	s_waitcnt lgkmcnt(0)
	v_mfma_f32_16x16x32_bf16 v[0:3], v[20:23], v[130:133], v[0:3]
	s_nop 1
	v_add_co_u32_e32 v68, vcc, s9, v120
	v_mfma_f32_16x16x32_bf16 v[96:99], v[12:15], v[130:133], v[4:7]
	s_nop 0
	v_addc_co_u32_e32 v69, vcc, -1, v121, vcc
	global_store_dwordx4 v[68:69], v[48:51], off offset:-3072
	v_mfma_f32_16x16x32_bf16 v[64:67], v[20:23], v[76:79], v[64:67]
	global_store_dwordx4 v[68:69], v[0:3], off
	v_cvt_pk_bf16_f32 v48, v108, v109
	v_cvt_pk_bf16_f32 v49, v110, v111
	ds_write2st64_b64 v127, v[48:49], v[16:17] offset0:16 offset1:18
	v_cvt_pk_bf16_f32 v16, v100, v101
	v_cvt_pk_bf16_f32 v17, v102, v103
	v_cvt_pk_bf16_f32 v0, v96, v97
	v_cvt_pk_bf16_f32 v1, v98, v99
	global_store_dwordx4 v[68:69], v[52:55], off offset:-2048
	global_store_dwordx4 v[68:69], v[64:67], off offset:-1024
	ds_write_b64 v128, v[16:17] offset:8192
	ds_write_b64 v129, v[0:1] offset:8192
	s_min_u32 s14, s13, 0x7d
	s_add_i32 s14, s14, s8
	s_ashr_i32 s15, s14, 31
	s_lshl_b64 s[16:17], s[14:15], 12
	v_lshl_add_u64 v[0:1], s[16:17], 0, v[112:113]
	v_lshlrev_b64 v[8:9], 1, v[0:1]
	v_lshl_add_u64 v[12:13], s[0:1], 0, v[8:9]
	v_lshl_add_u64 v[10:11], s[20:21], 0, v[8:9]
	v_lshl_add_u64 v[14:15], s[2:3], 0, v[8:9]
	global_load_dwordx4 v[4:7], v[12:13], off
	global_load_dwordx4 v[0:3], v[14:15], off
	v_lshl_add_u64 v[12:13], s[4:5], 0, v[8:9]
	v_lshl_add_u64 v[8:9], s[16:17], 0, v[114:115]
	v_lshlrev_b64 v[14:15], 1, v[8:9]
	v_lshl_add_u64 v[20:21], s[0:1], 0, v[14:15]
	v_lshl_add_u64 v[64:65], s[2:3], 0, v[14:15]
	s_lshl_b64 s[16:17], s[14:15], 14
	s_nop 0
	s_nop 0
	s_nop 0
	global_load_dwordx4 v[8:11], v[12:13], off
	global_load_dwordx4 v[16:19], v[20:21], off
	v_lshl_add_u64 v[66:67], s[4:5], 0, v[14:15]
	global_load_dwordx4 v[20:23], v[64:65], off
	global_load_dwordx4 v[12:15], v[66:67], off
	v_lshl_add_u64 v[64:65], v[116:117], 0, s[16:17]
	s_lshl_b64 s[14:15], s[14:15], 2
	s_nop 0
	s_nop 0
	s_nop 0
	s_nop 0
	s_nop 0
	s_add_u32 s14, s10, s14
	s_addc_u32 s15, s11, s15
	s_nop 0
	s_waitcnt lgkmcnt(0)
	s_barrier
	ds_read_b128 v[130:133], v126 offset:8192
	ds_read_b128 v[134:137], v126 offset:9216
	ds_read_b128 v[138:141], v126 offset:10240
	ds_read_b128 v[142:145], v126 offset:11264
	ds_read_b128 v[146:149], v126 offset:12288
	s_waitcnt vmcnt(27) lgkmcnt(4)
	v_mov_b32_e32 v60, v196
	v_mov_b32_e32 v61, v197
	v_mov_b32_e32 v62, v198
	v_mov_b32_e32 v63, v199
	v_mov_b32_e32 v56, v200
	v_mov_b32_e32 v57, v201
	v_mov_b32_e32 v58, v202
	v_mov_b32_e32 v59, v203
	v_mov_b32_e32 v92, v204
	v_mov_b32_e32 v93, v205
	v_mov_b32_e32 v94, v206
	v_mov_b32_e32 v95, v207
	v_mov_b32_e32 v88, v208
	v_mov_b32_e32 v89, v209
	v_mov_b32_e32 v90, v210
	v_mov_b32_e32 v91, v211
	v_mov_b32_e32 v84, v212
	v_mov_b32_e32 v85, v213
	v_mov_b32_e32 v86, v214
	v_mov_b32_e32 v87, v215
	v_mov_b32_e32 v80, v216
	v_mov_b32_e32 v81, v217
	v_mov_b32_e32 v82, v218
	v_mov_b32_e32 v83, v219
	v_mov_b32_e32 v122, v195
	v_mfma_f32_16x16x32_bf16 v[150:153], v[60:63], v[130:133], 0
	ds_read_b128 v[154:157], v126 offset:13312
	ds_read_b128 v[158:161], v126 offset:14336
	ds_read_b128 v[162:165], v126 offset:15360
	s_nop 0
	v_pk_mul_f32 v[102:103], v[122:123], v[102:103] op_sel_hi:[0,1]
	v_pk_mul_f32 v[100:101], v[122:123], v[100:101] op_sel_hi:[0,1]
	s_waitcnt lgkmcnt(3)
	v_mfma_f32_16x16x32_bf16 v[150:153], v[56:59], v[146:149], v[150:153]
	s_add_i32 s12, s12, 3
	v_mfma_f32_16x16x32_bf16 v[166:169], v[60:63], v[134:137], 0
	s_nop 0
	s_nop 4
	v_sub_f32_e32 v95, v95, v153
	v_sub_f32_e32 v94, v94, v152
	v_sub_f32_e32 v93, v93, v151
	v_sub_f32_e32 v92, v92, v150
	v_cvt_pk_bf16_f32 v150, v92, v93
	v_cvt_pk_bf16_f32 v151, v94, v95
	s_waitcnt lgkmcnt(2)
	v_mfma_f32_16x16x32_bf16 v[92:95], v[56:59], v[154:157], v[166:169]
	s_nop 0
	s_nop 6
	v_sub_f32_e32 v95, v91, v95
	v_sub_f32_e32 v94, v90, v94
	v_sub_f32_e32 v93, v89, v93
	v_sub_f32_e32 v92, v88, v92
	v_mfma_f32_16x16x32_bf16 v[88:91], v[60:63], v[138:141], 0
	v_cvt_pk_bf16_f32 v92, v92, v93
	v_cvt_pk_bf16_f32 v93, v94, v95
	ds_write2st64_b64 v127, v[150:151], v[92:93] offset0:32 offset1:34
	v_mfma_f32_16x16x32_bf16 v[60:63], v[60:63], v[142:145], 0
	v_mul_f32_e64 v94, v122, v110
	v_mul_f32_e64 v95, v122, v111
	v_pk_mul_f32 v[92:93], v[122:123], v[108:109] op_sel_hi:[0,1]
	s_waitcnt lgkmcnt(2)
	v_mfma_f32_16x16x32_bf16 v[88:91], v[56:59], v[158:161], v[88:91]
	s_waitcnt lgkmcnt(1)
	v_mfma_f32_16x16x32_bf16 v[56:59], v[56:59], v[162:165], v[60:63]
	s_nop 0
	s_nop 4
	v_sub_f32_e32 v87, v87, v91
	v_sub_f32_e32 v86, v86, v90
	v_sub_f32_e32 v85, v85, v89
	v_sub_f32_e32 v84, v84, v88
	s_nop 0
	v_sub_f32_e32 v59, v83, v59
	v_sub_f32_e32 v58, v82, v58
	v_sub_f32_e32 v57, v81, v57
	v_sub_f32_e32 v56, v80, v56
	v_cvt_pk_bf16_f32 v84, v84, v85
	v_cvt_pk_bf16_f32 v85, v86, v87
	v_cvt_pk_bf16_f32 v56, v56, v57
	v_cvt_pk_bf16_f32 v57, v58, v59
	ds_write_b64 v128, v[84:85] offset:16384
	ds_write_b64 v129, v[56:57] offset:16384
	s_waitcnt vmcnt(17)
	v_mfma_f32_16x16x32_bf16 v[56:59], v[28:31], v[130:133], 0
	s_waitcnt lgkmcnt(0)
	s_barrier
; __device__ __forceinline__ uint2 pack4v(f32x4 a) { uint2 r; r.x = pack2(a[0], a[1]); r.y = pack2(a[2], a[3]); return r; }
; __device__ __forceinline__ f32x4 mfma16(bf16x8 a, bf16x8 b, f32x4 c) { return __builtin_amdgcn_mfma_f32_16x16x32_bf16(a, b, c, 0, 0, 0); }
; __device__ __forceinline__ void scan_step(const ScanCtx& c, int n, const u16* Sc, u16* Sn, f32x4 (&S)[4], bf16x8 (&W_)[2], ...
;     ...
;   bf16x8 Vf[2][4];
; #pragma unroll
;   for (int kb = 0; kb < 2; ++kb)
; #pragma unroll
;     for (int nt = 0; nt < 4; ++nt) Vf[kb][nt] = *(const bf16x8*)(c.Vbuf + ((kb * 4 + nt) * 64 + lane) * 8);
;   const float glc = g_;
; #pragma unroll
;   for (int nt = 0; nt < 4; ++nt) {
;     f32x4 o = {0.f, 0.f, 0.f, 0.f};
;     o = mfma16(QH_[0], Sf[0][nt], o); o = mfma16(QH_[1], Sf[1][nt], o);
;     o = mfma16(QK_[0], Vf[0][nt], o); o = mfma16(QK_[1], Vf[1][nt], o);
;     *(f32x4*)(c.Obuf + cb + ((w * 4 + nt) * 64 + lane) * 4) = o;
;     f32x4 sv = S[nt] * glc;
;     sv = mfma16(KT_[0], Vf[0][nt], sv); sv = mfma16(KT_[1], Vf[1][nt], sv);
;     S[nt] = sv;
;     *(uint2*)(Sn + (((w >> 1) * 4 + nt) * 64 + lane) * 8 + (w & 1) * 4) = pack4v(sv);
;   }
;   __builtin_amdgcn_sched_barrier(0);
;   scan_load(c, n + 2, W_, QH_, QK_, KT_, U_, g_);
; __device__ void scan_seq(const P& p, int seq, u16* lds) {
;     ...
; #pragma unroll
;   for (int nt = 0; nt < 4; ++nt)
; #pragma unroll
;     for (int r = 0; r < 4; ++r) p.out[O_DP + ((size_t)seq * 64 + w * 16 + fq * 4 + r) * 64 + nt * 16 + fr] = S[nt][r];
	s_min_u32 s24, s12, 0x7d
	s_add_i32 s24, s24, s8
	s_ashr_i32 s25, s24, 31
	s_lshl_b64 s[26:27], s[24:25], 12
	v_lshl_add_u64 v[222:223], s[26:27], 0, v[112:113]
	v_lshlrev_b64 v[222:223], 1, v[222:223]
	v_lshl_add_u64 v[222:223], s[20:21], 0, v[222:223]
	s_lshl_b64 s[26:27], s[24:25], 14
	v_lshl_add_u64 v[224:225], v[116:117], 0, s[26:27]
	s_lshl_b64 s[28:29], s[24:25], 2
	s_add_u32 s28, s10, s28
	s_addc_u32 s29, s11, s29
	global_load_dwordx4 v[196:199], v[222:223], off
	global_load_dwordx4 v[200:203], v[222:223], off offset:1024
	global_load_dwordx4 v[204:207], v[224:225], off
	global_load_dwordx4 v[208:211], v[224:225], off offset:1024
	global_load_dwordx4 v[212:215], v[224:225], off offset:2048
	global_load_dwordx4 v[216:219], v[224:225], off offset:3072
	global_load_dword v195, v125, s[28:29]
	v_mfma_f32_16x16x32_bf16 v[56:59], v[40:43], v[146:149], v[56:59]
	ds_read_b128 v[60:63], v126 offset:16384
	ds_read_b128 v[80:83], v126 offset:17408
	ds_read_b128 v[84:87], v126 offset:20480
	ds_read_b128 v[88:91], v126 offset:21504
	s_waitcnt lgkmcnt(3)
	v_mfma_f32_16x16x32_bf16 v[56:59], v[24:27], v[60:63], v[56:59]
	v_mfma_f32_16x16x32_bf16 v[60:63], v[32:35], v[60:63], v[92:95]
	s_waitcnt lgkmcnt(1)
	v_mfma_f32_16x16x32_bf16 v[108:111], v[36:39], v[84:87], v[60:63]
	v_mfma_f32_16x16x32_bf16 v[60:63], v[28:31], v[134:137], 0
	v_mfma_f32_16x16x32_bf16 v[60:63], v[40:43], v[154:157], v[60:63]
	v_mfma_f32_16x16x32_bf16 v[56:59], v[44:47], v[84:87], v[56:59]
	v_mul_f32_e64 v86, v122, v106
	v_mul_f32_e64 v87, v122, v107
	v_pk_mul_f32 v[84:85], v[122:123], v[104:105] op_sel_hi:[0,1]
	v_mfma_f32_16x16x32_bf16 v[60:63], v[24:27], v[80:83], v[60:63]
	s_nop 0
	v_mfma_f32_16x16x32_bf16 v[80:83], v[32:35], v[80:83], v[84:87]
	s_waitcnt lgkmcnt(0)
	v_mfma_f32_16x16x32_bf16 v[104:107], v[36:39], v[88:91], v[80:83]
	v_mfma_f32_16x16x32_bf16 v[80:83], v[28:31], v[138:141], 0
	v_mfma_f32_16x16x32_bf16 v[28:31], v[28:31], v[142:145], 0
	v_mfma_f32_16x16x32_bf16 v[60:63], v[44:47], v[88:91], v[60:63]
	ds_read_b128 v[84:87], v126 offset:18432
	ds_read_b128 v[88:91], v126 offset:19456
	ds_read_b128 v[92:95], v126 offset:22528
	ds_read_b128 v[130:133], v126 offset:23552
	global_store_dwordx4 v[120:121], v[56:59], off offset:-3072
	v_mfma_f32_16x16x32_bf16 v[80:83], v[40:43], v[158:161], v[80:83]
	s_nop 1
	global_store_dwordx4 v[120:121], v[60:63], off offset:-2048
	v_cvt_pk_bf16_f32 v56, v108, v109
	v_cvt_pk_bf16_f32 v57, v110, v111
	v_mfma_f32_16x16x32_bf16 v[28:31], v[40:43], v[162:165], v[28:31]
	v_cvt_pk_bf16_f32 v40, v104, v105
	v_cvt_pk_bf16_f32 v41, v106, v107
	ds_write2st64_b64 v127, v[56:57], v[40:41] offset1:2
	s_waitcnt lgkmcnt(4)
	v_mfma_f32_16x16x32_bf16 v[80:83], v[24:27], v[84:87], v[80:83]
	s_waitcnt lgkmcnt(3)
	v_mfma_f32_16x16x32_bf16 v[24:27], v[24:27], v[88:91], v[28:31]
	s_nop 2
	v_mul_f32_e64 v30, v122, v98
	v_mul_f32_e64 v31, v122, v99
	v_pk_mul_f32 v[28:29], v[122:123], v[96:97] op_sel_hi:[0,1]
	v_mfma_f32_16x16x32_bf16 v[84:87], v[32:35], v[84:87], v[100:103]
	s_nop 0
	v_mfma_f32_16x16x32_bf16 v[28:31], v[32:35], v[88:91], v[28:31]
	s_waitcnt lgkmcnt(2)
	v_mfma_f32_16x16x32_bf16 v[100:103], v[36:39], v[92:95], v[84:87]
	s_waitcnt lgkmcnt(1)
	v_mfma_f32_16x16x32_bf16 v[24:27], v[44:47], v[130:133], v[24:27]
	v_mfma_f32_16x16x32_bf16 v[96:99], v[36:39], v[130:133], v[28:31]
	s_nop 4
	v_cvt_pk_bf16_f32 v40, v100, v101
	v_cvt_pk_bf16_f32 v41, v102, v103
	global_store_dwordx4 v[120:121], v[24:27], off
	v_mfma_f32_16x16x32_bf16 v[80:83], v[44:47], v[92:95], v[80:83]
	ds_write_b64 v128, v[40:41]
	v_cvt_pk_bf16_f32 v24, v96, v97
	v_cvt_pk_bf16_f32 v25, v98, v99
	ds_write_b64 v129, v[24:25]
	s_nop 3
	global_store_dwordx4 v[120:121], v[80:83], off offset:-1024
	s_min_u32 s12, s12, 0x7d
	s_add_i32 s14, s12, s8
	s_ashr_i32 s15, s14, 31
	s_lshl_b64 s[16:17], s[14:15], 12
	v_lshl_add_u64 v[24:25], s[16:17], 0, v[112:113]
	v_lshlrev_b64 v[32:33], 1, v[24:25]
	v_lshl_add_u64 v[34:35], s[20:21], 0, v[32:33]
	v_lshl_add_u64 v[24:25], s[0:1], 0, v[32:33]
	v_lshl_add_u64 v[26:27], s[2:3], 0, v[32:33]
	v_lshl_add_u64 v[36:37], s[4:5], 0, v[32:33]
	v_lshl_add_u64 v[32:33], s[16:17], 0, v[114:115]
	v_lshlrev_b64 v[38:39], 1, v[32:33]
	v_lshl_add_u64 v[44:45], s[0:1], 0, v[38:39]
	v_lshl_add_u64 v[80:81], s[2:3], 0, v[38:39]
	s_lshl_b64 s[16:17], s[14:15], 14
	global_load_dwordx4 v[28:31], v[24:25], off
	s_nop 0
	global_load_dwordx4 v[24:27], v[26:27], off
	s_nop 0
	s_nop 0
	s_nop 0
	s_nop 0
	global_load_dwordx4 v[32:35], v[36:37], off
	global_load_dwordx4 v[40:43], v[44:45], off
	v_lshl_add_u64 v[82:83], s[4:5], 0, v[38:39]
	global_load_dwordx4 v[44:47], v[80:81], off
	global_load_dwordx4 v[36:39], v[82:83], off
	v_lshl_add_u64 v[80:81], v[116:117], 0, s[16:17]
	s_lshl_b64 s[14:15], s[14:15], 2
	s_nop 0
	s_nop 0
	s_nop 0
	s_nop 0
	s_nop 0
	s_add_u32 s14, s10, s14
	s_addc_u32 s15, s11, s15
	s_nop 0
	v_lshl_add_u64 v[120:121], v[120:121], 0, s[6:7]
	s_cmpk_lt_u32 s13, 0x7e
	s_mov_b32 s12, s13
	s_waitcnt lgkmcnt(0)
	s_barrier
	s_cbranch_scc1 .LBB0_483
	v_readlane_b32 s0, v228, 0
	v_readlane_b32 s1, v228, 1
	s_mov_b32 s2, s0
	s_ashr_i32 s3, s0, 31
	v_writelane_b32 v228, s0, 0
	s_waitcnt vmcnt(0)
	v_lshlrev_b32_e32 v0, 4, v124
	v_ashrrev_i32_e32 v1, 31, v0
	v_writelane_b32 v228, s1, 1
	s_lshl_b64 s[0:1], s[2:3], 6
	v_lshl_add_u64 v[0:1], s[0:1], 0, v[0:1]
	v_lshrrev_b32_e32 v3, 2, v123
	v_and_or_b32 v0, v3, 12, v0
	v_and_b32_e32 v2, 15, v123
	v_lshlrev_b64 v[0:1], 8, v[0:1]
	v_lshl_add_u64 v[0:1], s[20:21], 0, v[0:1]
	v_lshlrev_b32_e32 v2, 2, v2
	v_mov_b32_e32 v3, 0
	v_lshl_add_u64 v[0:1], v[0:1], 0, v[2:3]
	s_mov_b32 s0, 0x8492000
	v_add_co_u32_e32 v0, vcc, s0, v0
	s_nop 1
	v_addc_co_u32_e32 v1, vcc, 0, v1, vcc
	global_store_dword v[0:1], v108, off
	global_store_dword v[0:1], v109, off offset:256
	global_store_dword v[0:1], v110, off offset:512
	global_store_dword v[0:1], v111, off offset:768
	global_store_dword v[0:1], v104, off offset:64
	global_store_dword v[0:1], v105, off offset:320
	global_store_dword v[0:1], v106, off offset:576
	global_store_dword v[0:1], v107, off offset:832
	global_store_dword v[0:1], v100, off offset:128
	global_store_dword v[0:1], v101, off offset:384
	global_store_dword v[0:1], v102, off offset:640
	global_store_dword v[0:1], v103, off offset:896
	global_store_dword v[0:1], v96, off offset:192
	global_store_dword v[0:1], v97, off offset:448
	global_store_dword v[0:1], v98, off offset:704
	global_store_dword v[0:1], v99, off offset:960
